# P6 walks its tile sequence backwards (starts with the MIX rows P5 wrote last)
# speedup vs baseline: 1.0117x; 1.0016x over previous
;     __device__ bool next(int i, Unit& u) const { if (!so.next(i >> 1, u)) return false; u.sel = i & 1; return true; }
;     __host__ __device__ bool next(int i, Unit& u) const {
;         const long L = (long)i * G + c; if (L >= nwg) return false;
;         int wgid = (int)L; { const int q = nwg / NXCD, r = nwg % NXCD, xcd = wgid % NXCD, off = wgid / NXCD; wgid = (xcd < r ? xcd * (q + 1) : r * (q + 1) + (xcd - r) * q) + off; }
;         const int nig = WGM * nN, gid = wgid / nig, fm = gid * WGM, gsz = (nM - fm) < WGM ? (nM - fm) : WGM;
;         u.pm = fm + ((wgid % nig) % gsz); u.pn = (wgid % nig) / gsz; u.sel = 0; return true;
.LBB0_851:
	s_or_b64 exec, exec, s[0:1]
	v_mov_b32_e32 v12, v201
	s_waitcnt lgkmcnt(0)
	s_barrier
	s_movk_i32 s0, 0x400
	v_readfirstlane_b32 s6, v12
	s_and_b64 vcc, exec, s[8:9]
	s_cbranch_vccnz .LBB0_857
	s_sub_u32 s99, 0x3ff, s2
	s_ashr_i32 s1, s99, 31
	s_lshr_b32 s1, s1, 29
	s_add_i32 s1, s99, s1
	s_and_b32 s3, s1, -8
	s_sub_i32 s3, s99, s3
	s_cmp_gt_i32 s3, -1
	s_cbranch_scc0 .LBB0_854
	s_lshl_b32 s7, s3, 7
	s_cbranch_execz .LBB0_855
	s_branch .LBB0_856

;     __device__ bool next(int i, Unit& u) const { if (!so.next(i >> 1, u)) return false; u.sel = i & 1; return true; }
;     __host__ __device__ bool next(int i, Unit& u) const {
;         const long L = (long)i * G + c; if (L >= nwg) return false;
;         int wgid = (int)L; { const int q = nwg / NXCD, r = nwg % NXCD, xcd = wgid % NXCD, off = wgid / NXCD; wgid = (xcd < r ? xcd * (q + 1) : r * (q + 1) + (xcd - r) * q) + off; }
;         const int nig = WGM * nN, gid = wgid / nig, fm = gid * WGM, gsz = (nM - fm) < WGM ? (nM - fm) : WGM;
;         u.pm = fm + ((wgid % nig) % gsz); u.pn = (wgid % nig) / gsz; u.sel = 0; return true;
; template <class Epi, class Sched, bool ALIGN_EPI = false, bool SP2 = false>
; __device__ __forceinline__ void gemm_phase(PG8_LAS unsigned char* lds, const Gemm g, const Sched& S, const Epi& E) {
;     ...
;         const bool has_next = S.next(ui + 1, nxt);
.LBB0_863:
	s_add_i32 s74, s74, 1
	s_mul_i32 s0, s74, s69
	s_mul_hi_u32 s1, s74, s70
	s_add_i32 s1, s1, s0
	s_mul_i32 s0, s74, s70
	s_add_u32 s6, s0, s2
	s_addc_u32 s7, s1, s71
	v_cmp_gt_i64_e32 vcc, s[6:7], v[142:143]
	v_cmp_lt_i64_e64 s[0:1], s[6:7], v[140:141]
	s_cbranch_vccnz .LBB0_869
	s_sub_u32 s6, 0x3ff, s6
	s_ashr_i32 s7, s6, 31
	s_lshr_b32 s7, s7, 29
	s_add_i32 s48, s6, s7
	s_and_b32 s7, s48, -8
	s_sub_i32 s49, s6, s7
	s_cmp_gt_i32 s49, -1
	s_mov_b64 s[6:7], -1
	s_cbranch_scc0 .LBB0_866
	s_lshl_b32 s75, s49, 7
	s_mov_b64 s[6:7], 0
